# v89 stack + P1 k/v column tiles (scale exactly 1.0): separate epilogue path that skips the 64 multiplies by 1.0 and converts the accumulators directly
# speedup vs baseline: 1.0049x; 1.0049x over previous
; __device__ __forceinline__ u32x4 pack8(f32x4 v0, f32x4 v1) { u32x4 w; w.x = cvt_pk_bf16(v0[0], v0[1]); w.y = cvt_pk_bf16(v0[2], v0[3]); w.z = cvt_pk_bf16(v1[0], v1[1]); w.w = cvt_pk_bf16(v1[2], v1[3]); return w; }
;     __device__ __forceinline__ void operator()(Acc& acc, const Unit& u, int wr, int wc, int fr, int fq, PG8_LAS unsigned char*) const {
;     ...
;         } else {
;             const float s = (u.c0 < 1536) ? sc : 1.f;
;             bf16_t* base = O + (size_t)(u.r0 + wr * 64 + fr) * ldc + u.c0 + wc * 32 + 8 * fq;
; #pragma unroll
;             for (int ai = 0; ai < 2; ++ai)
; #pragma unroll
;                 for (int m = 0; m < 4; ++m) { bf16_t* rowp = base + (size_t)(ai * HALF + m * 16) * ldc;
; #pragma unroll
;                     for (int bj = 0; bj < 2; ++bj) *(u32x4*)(rowp + bj * HALF) = pack8(acc[ai][bj][m][0] * s, acc[ai][bj][m][1] * s); }
.LBB0_108:
	s_cmpk_lt_u32 s6, 0x600
	v_mov_b64_e32 v[150:151], s[10:11]
	s_cselect_b64 vcc, -1, 0
	s_cbranch_vccz .Lqkv_ns
	v_mad_i64_i32 v[150:151], s[26:27], v149, s62, v[150:151]
	v_cndmask_b32_e32 v148, 1.0, v156, vcc
	v_lshl_add_u64 v[150:151], s[6:7], 1, v[150:151]
	s_lshl_b32 s26, s57, 1
	s_mov_b32 s27, s7
	v_lshl_add_u64 v[150:151], v[150:151], 0, s[26:27]
	v_pk_mul_f32 v[160:161], v[148:149], v[126:127] op_sel_hi:[0,1]
	v_pk_mul_f32 v[158:159], v[148:149], v[124:125] op_sel_hi:[0,1]
	v_lshl_add_u64 v[150:151], v[150:151], 0, v[136:137]
	v_pk_mul_f32 v[162:163], v[148:149], v[118:119] op_sel_hi:[0,1]
	v_pk_mul_f32 v[164:165], v[148:149], v[116:117] op_sel_hi:[0,1]
	v_cvt_pk_bf16_f32 v158, v158, v159
	v_cvt_pk_bf16_f32 v159, v160, v161
	v_cvt_pk_bf16_f32 v160, v164, v165
	v_cvt_pk_bf16_f32 v161, v162, v163
	flat_store_dwordx4 v[150:151], v[158:161]
	v_pk_mul_f32 v[162:163], v[148:149], v[114:115] op_sel_hi:[0,1]
	v_pk_mul_f32 v[164:165], v[148:149], v[112:113] op_sel_hi:[0,1]
	v_pk_mul_f32 v[160:161], v[148:149], v[122:123] op_sel_hi:[0,1]
	v_pk_mul_f32 v[158:159], v[148:149], v[120:121] op_sel_hi:[0,1]
	v_cvt_pk_bf16_f32 v158, v158, v159
	v_cvt_pk_bf16_f32 v159, v160, v161
	v_cvt_pk_bf16_f32 v160, v164, v165
	v_cvt_pk_bf16_f32 v161, v162, v163
	flat_store_dwordx4 v[150:151], v[158:161] offset:256
	v_pk_mul_f32 v[162:163], v[148:149], v[102:103] op_sel_hi:[0,1]
	v_pk_mul_f32 v[164:165], v[148:149], v[100:101] op_sel_hi:[0,1]
	v_pk_mul_f32 v[160:161], v[148:149], v[110:111] op_sel_hi:[0,1]
	v_pk_mul_f32 v[158:159], v[148:149], v[108:109] op_sel_hi:[0,1]
	v_cvt_pk_bf16_f32 v158, v158, v159
	v_cvt_pk_bf16_f32 v159, v160, v161
	v_cvt_pk_bf16_f32 v160, v164, v165
	v_cvt_pk_bf16_f32 v161, v162, v163
	v_add_co_u32_e32 v162, vcc, s56, v150
	v_pk_mul_f32 v[164:165], v[148:149], v[98:99] op_sel_hi:[0,1]
	s_nop 0
	v_addc_co_u32_e32 v163, vcc, 0, v151, vcc
	flat_store_dwordx4 v[162:163], v[158:161]
	v_pk_mul_f32 v[166:167], v[148:149], v[96:97] op_sel_hi:[0,1]
	s_nop 0
	v_pk_mul_f32 v[160:161], v[148:149], v[106:107] op_sel_hi:[0,1]
	v_pk_mul_f32 v[158:159], v[148:149], v[104:105] op_sel_hi:[0,1]
	v_cvt_pk_bf16_f32 v158, v158, v159
	v_cvt_pk_bf16_f32 v159, v160, v161
	v_cvt_pk_bf16_f32 v160, v166, v167
	v_cvt_pk_bf16_f32 v161, v164, v165
	flat_store_dwordx4 v[162:163], v[158:161] offset:256
	v_pk_mul_f32 v[162:163], v[148:149], v[86:87] op_sel_hi:[0,1]
	v_pk_mul_f32 v[164:165], v[148:149], v[84:85] op_sel_hi:[0,1]
	v_pk_mul_f32 v[160:161], v[148:149], v[94:95] op_sel_hi:[0,1]
	v_pk_mul_f32 v[158:159], v[148:149], v[92:93] op_sel_hi:[0,1]
	v_cvt_pk_bf16_f32 v158, v158, v159
	v_cvt_pk_bf16_f32 v159, v160, v161
	v_cvt_pk_bf16_f32 v160, v164, v165
	v_cvt_pk_bf16_f32 v161, v162, v163
	v_add_co_u32_e32 v162, vcc, s63, v150
	v_pk_mul_f32 v[164:165], v[148:149], v[82:83] op_sel_hi:[0,1]
	s_nop 0
	v_addc_co_u32_e32 v163, vcc, 0, v151, vcc
	flat_store_dwordx4 v[162:163], v[158:161]
	v_pk_mul_f32 v[166:167], v[148:149], v[80:81] op_sel_hi:[0,1]
	s_nop 0
	v_pk_mul_f32 v[160:161], v[148:149], v[90:91] op_sel_hi:[0,1]
	v_pk_mul_f32 v[158:159], v[148:149], v[88:89] op_sel_hi:[0,1]
	v_cvt_pk_bf16_f32 v158, v158, v159
	v_cvt_pk_bf16_f32 v159, v160, v161
	v_cvt_pk_bf16_f32 v160, v166, v167
	v_cvt_pk_bf16_f32 v161, v164, v165
	flat_store_dwordx4 v[162:163], v[158:161] offset:256
	v_pk_mul_f32 v[162:163], v[148:149], v[70:71] op_sel_hi:[0,1]
	v_pk_mul_f32 v[164:165], v[148:149], v[68:69] op_sel_hi:[0,1]
	v_pk_mul_f32 v[160:161], v[148:149], v[78:79] op_sel_hi:[0,1]
	v_pk_mul_f32 v[158:159], v[148:149], v[76:77] op_sel_hi:[0,1]
	v_cvt_pk_bf16_f32 v158, v158, v159
	v_cvt_pk_bf16_f32 v159, v160, v161
	v_cvt_pk_bf16_f32 v160, v164, v165
	v_cvt_pk_bf16_f32 v161, v162, v163
	v_add_co_u32_e32 v162, vcc, s64, v150
	v_pk_mul_f32 v[164:165], v[148:149], v[66:67] op_sel_hi:[0,1]
	s_nop 0
	v_addc_co_u32_e32 v163, vcc, 0, v151, vcc
	flat_store_dwordx4 v[162:163], v[158:161]
	v_pk_mul_f32 v[166:167], v[148:149], v[64:65] op_sel_hi:[0,1]
	s_nop 0
	v_pk_mul_f32 v[160:161], v[148:149], v[74:75] op_sel_hi:[0,1]
	v_pk_mul_f32 v[158:159], v[148:149], v[72:73] op_sel_hi:[0,1]
	v_cvt_pk_bf16_f32 v158, v158, v159
	v_cvt_pk_bf16_f32 v159, v160, v161
	v_cvt_pk_bf16_f32 v160, v166, v167
	v_cvt_pk_bf16_f32 v161, v164, v165
	flat_store_dwordx4 v[162:163], v[158:161] offset:256
	v_pk_mul_f32 v[162:163], v[148:149], v[54:55] op_sel_hi:[0,1]
	v_pk_mul_f32 v[164:165], v[148:149], v[52:53] op_sel_hi:[0,1]
	v_pk_mul_f32 v[160:161], v[148:149], v[62:63] op_sel_hi:[0,1]
	v_pk_mul_f32 v[158:159], v[148:149], v[60:61] op_sel_hi:[0,1]
	v_cvt_pk_bf16_f32 v158, v158, v159
	v_cvt_pk_bf16_f32 v159, v160, v161
	v_cvt_pk_bf16_f32 v160, v164, v165
	v_cvt_pk_bf16_f32 v161, v162, v163
	v_add_co_u32_e32 v162, vcc, s65, v150
	v_pk_mul_f32 v[164:165], v[148:149], v[50:51] op_sel_hi:[0,1]
	s_nop 0
	v_addc_co_u32_e32 v163, vcc, 0, v151, vcc
	flat_store_dwordx4 v[162:163], v[158:161]
	v_pk_mul_f32 v[166:167], v[148:149], v[48:49] op_sel_hi:[0,1]
	s_nop 0
	v_pk_mul_f32 v[160:161], v[148:149], v[58:59] op_sel_hi:[0,1]
	v_pk_mul_f32 v[158:159], v[148:149], v[56:57] op_sel_hi:[0,1]
	v_cvt_pk_bf16_f32 v158, v158, v159
	v_cvt_pk_bf16_f32 v159, v160, v161
	v_cvt_pk_bf16_f32 v160, v166, v167
	v_cvt_pk_bf16_f32 v161, v164, v165
	flat_store_dwordx4 v[162:163], v[158:161] offset:256
	v_pk_mul_f32 v[162:163], v[148:149], v[38:39] op_sel_hi:[0,1]
	v_pk_mul_f32 v[164:165], v[148:149], v[36:37] op_sel_hi:[0,1]
	v_pk_mul_f32 v[160:161], v[148:149], v[46:47] op_sel_hi:[0,1]
	v_pk_mul_f32 v[158:159], v[148:149], v[44:45] op_sel_hi:[0,1]
	v_cvt_pk_bf16_f32 v158, v158, v159
	v_cvt_pk_bf16_f32 v159, v160, v161
	v_cvt_pk_bf16_f32 v160, v164, v165
; __device__ __forceinline__ u32x4 pack8(f32x4 v0, f32x4 v1) { u32x4 w; w.x = cvt_pk_bf16(v0[0], v0[1]); w.y = cvt_pk_bf16(v0[2], v0[3]); w.z = cvt_pk_bf16(v1[0], v1[1]); w.w = cvt_pk_bf16(v1[2], v1[3]); return w; }
;     __device__ __forceinline__ void operator()(Acc& acc, const Unit& u, int wr, int wc, int fr, int fq, PG8_LAS unsigned char*) const {
;     ...
;         } else {
;             const float s = (u.c0 < 1536) ? sc : 1.f;
;             bf16_t* base = O + (size_t)(u.r0 + wr * 64 + fr) * ldc + u.c0 + wc * 32 + 8 * fq;
; #pragma unroll
;             for (int ai = 0; ai < 2; ++ai)
; #pragma unroll
;                 for (int m = 0; m < 4; ++m) { bf16_t* rowp = base + (size_t)(ai * HALF + m * 16) * ldc;
; #pragma unroll
;                     for (int bj = 0; bj < 2; ++bj) *(u32x4*)(rowp + bj * HALF) = pack8(acc[ai][bj][m][0] * s, acc[ai][bj][m][1] * s); }
	v_cvt_pk_bf16_f32 v161, v162, v163
	v_add_co_u32_e32 v162, vcc, s66, v150
	v_pk_mul_f32 v[164:165], v[148:149], v[34:35] op_sel_hi:[0,1]
	s_nop 0
	v_addc_co_u32_e32 v163, vcc, 0, v151, vcc
	flat_store_dwordx4 v[162:163], v[158:161]
	v_pk_mul_f32 v[166:167], v[148:149], v[32:33] op_sel_hi:[0,1]
	s_nop 0
	v_pk_mul_f32 v[160:161], v[148:149], v[42:43] op_sel_hi:[0,1]
	v_pk_mul_f32 v[158:159], v[148:149], v[40:41] op_sel_hi:[0,1]
	v_cvt_pk_bf16_f32 v158, v158, v159
	v_cvt_pk_bf16_f32 v159, v160, v161
	v_cvt_pk_bf16_f32 v160, v166, v167
	v_cvt_pk_bf16_f32 v161, v164, v165
	flat_store_dwordx4 v[162:163], v[158:161] offset:256
	v_pk_mul_f32 v[162:163], v[148:149], v[22:23] op_sel_hi:[0,1]
	v_pk_mul_f32 v[164:165], v[148:149], v[20:21] op_sel_hi:[0,1]
	v_pk_mul_f32 v[160:161], v[148:149], v[30:31] op_sel_hi:[0,1]
	v_pk_mul_f32 v[158:159], v[148:149], v[28:29] op_sel_hi:[0,1]
	v_cvt_pk_bf16_f32 v158, v158, v159
	v_cvt_pk_bf16_f32 v159, v160, v161
	v_cvt_pk_bf16_f32 v160, v164, v165
	v_cvt_pk_bf16_f32 v161, v162, v163
	v_add_co_u32_e32 v162, vcc, s67, v150
	v_pk_mul_f32 v[164:165], v[148:149], v[18:19] op_sel_hi:[0,1]
	s_nop 0
	v_addc_co_u32_e32 v163, vcc, 0, v151, vcc
	flat_store_dwordx4 v[162:163], v[158:161]
	v_pk_mul_f32 v[166:167], v[148:149], v[16:17] op_sel_hi:[0,1]
	v_add_co_u32_e32 v150, vcc, s70, v150
	v_pk_mul_f32 v[160:161], v[148:149], v[26:27] op_sel_hi:[0,1]
	v_pk_mul_f32 v[158:159], v[148:149], v[24:25] op_sel_hi:[0,1]
	v_cvt_pk_bf16_f32 v158, v158, v159
	v_cvt_pk_bf16_f32 v159, v160, v161
	v_cvt_pk_bf16_f32 v160, v166, v167
	v_cvt_pk_bf16_f32 v161, v164, v165
	flat_store_dwordx4 v[162:163], v[158:161] offset:256
	v_pk_mul_f32 v[162:163], v[148:149], v[6:7] op_sel_hi:[0,1]
	v_pk_mul_f32 v[164:165], v[148:149], v[4:5] op_sel_hi:[0,1]
	v_pk_mul_f32 v[160:161], v[148:149], v[14:15] op_sel_hi:[0,1]
	v_pk_mul_f32 v[158:159], v[148:149], v[12:13] op_sel_hi:[0,1]
	v_cvt_pk_bf16_f32 v158, v158, v159
	v_cvt_pk_bf16_f32 v159, v160, v161
	v_cvt_pk_bf16_f32 v160, v164, v165
	v_cvt_pk_bf16_f32 v161, v162, v163
	v_addc_co_u32_e32 v151, vcc, 0, v151, vcc
	flat_store_dwordx4 v[150:151], v[158:161]
	v_pk_mul_f32 v[162:163], v[148:149], v[2:3] op_sel_hi:[0,1]
	v_pk_mul_f32 v[164:165], v[148:149], v[0:1] op_sel_hi:[0,1]
	v_pk_mul_f32 v[160:161], v[148:149], v[10:11] op_sel_hi:[0,1]
	v_pk_mul_f32 v[158:159], v[148:149], v[8:9] op_sel_hi:[0,1]
	v_cvt_pk_bf16_f32 v158, v158, v159
	v_cvt_pk_bf16_f32 v159, v160, v161
	v_cvt_pk_bf16_f32 v160, v164, v165
	v_cvt_pk_bf16_f32 v161, v162, v163
	flat_store_dwordx4 v[150:151], v[158:161] offset:256
	s_cbranch_execnz .LBB0_107
.Lqkv_ns:
	v_mad_i64_i32 v[150:151], s[26:27], v149, s62, v[150:151]
	v_lshl_add_u64 v[150:151], s[6:7], 1, v[150:151]
	s_lshl_b32 s26, s57, 1
	s_mov_b32 s27, s7
	v_lshl_add_u64 v[150:151], v[150:151], 0, s[26:27]
	v_lshl_add_u64 v[150:151], v[150:151], 0, v[136:137]
	v_cvt_pk_bf16_f32 v158, v124, v125
	v_cvt_pk_bf16_f32 v159, v126, v127
	v_cvt_pk_bf16_f32 v160, v116, v117
	v_cvt_pk_bf16_f32 v161, v118, v119
	flat_store_dwordx4 v[150:151], v[158:161]
	s_nop 1
	v_cvt_pk_bf16_f32 v158, v120, v121
	v_cvt_pk_bf16_f32 v159, v122, v123
	v_cvt_pk_bf16_f32 v160, v112, v113
	v_cvt_pk_bf16_f32 v161, v114, v115
	flat_store_dwordx4 v[150:151], v[158:161] offset:256
	s_nop 1
	v_cvt_pk_bf16_f32 v158, v108, v109
	v_cvt_pk_bf16_f32 v159, v110, v111
	v_cvt_pk_bf16_f32 v160, v100, v101
	v_cvt_pk_bf16_f32 v161, v102, v103
	v_add_co_u32_e32 v162, vcc, s56, v150
	s_nop 0
	v_addc_co_u32_e32 v163, vcc, 0, v151, vcc
	flat_store_dwordx4 v[162:163], v[158:161]
	s_nop 1
	s_nop 0
	v_cvt_pk_bf16_f32 v158, v104, v105
	v_cvt_pk_bf16_f32 v159, v106, v107
	v_cvt_pk_bf16_f32 v160, v96, v97
	v_cvt_pk_bf16_f32 v161, v98, v99
	flat_store_dwordx4 v[162:163], v[158:161] offset:256
	s_nop 1
	v_cvt_pk_bf16_f32 v158, v92, v93
	v_cvt_pk_bf16_f32 v159, v94, v95
	v_cvt_pk_bf16_f32 v160, v84, v85
	v_cvt_pk_bf16_f32 v161, v86, v87
	v_add_co_u32_e32 v162, vcc, s63, v150
	s_nop 0
	v_addc_co_u32_e32 v163, vcc, 0, v151, vcc
	flat_store_dwordx4 v[162:163], v[158:161]
	s_nop 1
	s_nop 0
	v_cvt_pk_bf16_f32 v158, v88, v89
	v_cvt_pk_bf16_f32 v159, v90, v91
	v_cvt_pk_bf16_f32 v160, v80, v81
	v_cvt_pk_bf16_f32 v161, v82, v83
	flat_store_dwordx4 v[162:163], v[158:161] offset:256
	s_nop 1
	v_cvt_pk_bf16_f32 v158, v76, v77
	v_cvt_pk_bf16_f32 v159, v78, v79
	v_cvt_pk_bf16_f32 v160, v68, v69
	v_cvt_pk_bf16_f32 v161, v70, v71
	v_add_co_u32_e32 v162, vcc, s64, v150
	s_nop 0
	v_addc_co_u32_e32 v163, vcc, 0, v151, vcc
	flat_store_dwordx4 v[162:163], v[158:161]
	s_nop 1
	s_nop 0
	v_cvt_pk_bf16_f32 v158, v72, v73
	v_cvt_pk_bf16_f32 v159, v74, v75
	v_cvt_pk_bf16_f32 v160, v64, v65
	v_cvt_pk_bf16_f32 v161, v66, v67
	flat_store_dwordx4 v[162:163], v[158:161] offset:256
	s_nop 1
	v_cvt_pk_bf16_f32 v158, v60, v61
	v_cvt_pk_bf16_f32 v159, v62, v63
	v_cvt_pk_bf16_f32 v160, v52, v53
	v_cvt_pk_bf16_f32 v161, v54, v55
	v_add_co_u32_e32 v162, vcc, s65, v150
	s_nop 0
	v_addc_co_u32_e32 v163, vcc, 0, v151, vcc
	flat_store_dwordx4 v[162:163], v[158:161]
	s_nop 1
	s_nop 0
	v_cvt_pk_bf16_f32 v158, v56, v57
	v_cvt_pk_bf16_f32 v159, v58, v59
	v_cvt_pk_bf16_f32 v160, v48, v49
	v_cvt_pk_bf16_f32 v161, v50, v51
	flat_store_dwordx4 v[162:163], v[158:161] offset:256
	s_nop 1
	v_cvt_pk_bf16_f32 v158, v44, v45
	v_cvt_pk_bf16_f32 v159, v46, v47
	v_cvt_pk_bf16_f32 v160, v36, v37
	v_cvt_pk_bf16_f32 v161, v38, v39
	v_add_co_u32_e32 v162, vcc, s66, v150
	s_nop 0
	v_addc_co_u32_e32 v163, vcc, 0, v151, vcc
	flat_store_dwordx4 v[162:163], v[158:161]
	s_nop 1
	s_nop 0
	v_cvt_pk_bf16_f32 v158, v40, v41
	v_cvt_pk_bf16_f32 v159, v42, v43
	v_cvt_pk_bf16_f32 v160, v32, v33
	v_cvt_pk_bf16_f32 v161, v34, v35
	flat_store_dwordx4 v[162:163], v[158:161] offset:256
	s_nop 1
	v_cvt_pk_bf16_f32 v158, v28, v29
	v_cvt_pk_bf16_f32 v159, v30, v31
	v_cvt_pk_bf16_f32 v160, v20, v21
	v_cvt_pk_bf16_f32 v161, v22, v23
	v_add_co_u32_e32 v162, vcc, s67, v150
	s_nop 0
	v_addc_co_u32_e32 v163, vcc, 0, v151, vcc
	flat_store_dwordx4 v[162:163], v[158:161]
	s_nop 1
	v_add_co_u32_e32 v150, vcc, s70, v150
	v_cvt_pk_bf16_f32 v158, v24, v25
	v_cvt_pk_bf16_f32 v159, v26, v27
	v_cvt_pk_bf16_f32 v160, v16, v17
	v_cvt_pk_bf16_f32 v161, v18, v19
	flat_store_dwordx4 v[162:163], v[158:161] offset:256
	s_nop 1
	v_cvt_pk_bf16_f32 v158, v12, v13
	v_cvt_pk_bf16_f32 v159, v14, v15
	v_cvt_pk_bf16_f32 v160, v4, v5
	v_cvt_pk_bf16_f32 v161, v6, v7
	v_addc_co_u32_e32 v151, vcc, 0, v151, vcc
	flat_store_dwordx4 v[150:151], v[158:161]
	s_nop 1
	v_cvt_pk_bf16_f32 v158, v8, v9
	v_cvt_pk_bf16_f32 v159, v10, v11
	v_cvt_pk_bf16_f32 v160, v0, v1
	v_cvt_pk_bf16_f32 v161, v2, v3
	flat_store_dwordx4 v[150:151], v[158:161] offset:256
	s_nop 1
	s_branch .LBB0_107
